# v65 + closing s_setprio 0 issued behind the closing barrier (compute wave reaches the barrier one instruction earlier)
# baseline (speedup 1.0000x reference)
; template <class Epi, int AMODE>
; __device__ __forceinline__ void gemm_phase(LAS unsigned char* lds, const Gemm g, const StaticOrder& S, const Epi& E, int stagger_us, int tid_in) {
;     ...
;         for (int a = 0; a < 2; ++a)
; #pragma unroll
;             for (int b = 0; b < 2; ++b)
; #pragma unroll
;                 for (int m = 0; m < 4; ++m)
; #pragma unroll
;                     for (int n = 0; n < 2; ++n) acc[a][b][m][n] = (f32x4){0.f, 0.f, 0.f, 0.f};
;     __device__ __forceinline__ void operator()(f32x4 (&acc)[2][2][4][2], const Unit& u, int wr, int wc, int fr, int fq) const {
;     ...
;             const int tq = tok0 + 8 * fr; const int tA = tq < 0 ? 0 : (tq > TOK - 1 ? TOK - 1 : tq), tB = (tq + 7) > TOK - 1 ? TOK - 1 : (tq + 7);
;             const int bA = batch_of(tA), bB = batch_of(tB); const bool same = __all(bA == bB);
;             const float* bp0 = bias + 256 * u.pn + 32 * wc + 8 * fq;
;             f32x4 bvA[2][2]; float sq[8];
; #pragma unroll
;             for (int am = 0; am < 8; ++am) { int tok = tq + am; tok = tok < 0 ? 0 : (tok > TOK - 1 ? TOK - 1 : tok); sq[am] = LDG(float, ssq + tok); }
; #pragma unroll
;             for (int bj = 0; bj < 2; ++bj)
; #pragma unroll
;                 for (int n = 0; n < 2; ++n) bvA[bj][n] = LDG(f32x4, bp0 + (size_t)bA * (2 * DFF) + bj * HALF + 4 * n);
.LBB0_1298:
	s_ashr_i32 s47, s46, 31
	s_lshl_b64 s[6:7], s[46:47], 20
	s_add_u32 s96, s9, s6
	s_addc_u32 s97, s72, s7
	s_and_b64 s[6:7], s[42:43], exec
	s_cselect_b32 s27, s97, s5
	s_cselect_b32 s28, s96, s4
	s_add_u32 s29, s4, 0x100
	v_mov_b32_e32 v2, 0
	s_addc_u32 s30, s5, 0
	s_mov_b32 s31, -2
	s_mul_i32 s6, s26, 0xfc
	v_add_u32_e32 v222, s6, v197
	v_med3_i32 v240, v222, 0, v238
	v_add_u32_e32 v241, 0xffffe000, v240
	v_lshrrev_b32_e32 v241, 12, v241
	v_add_u32_e32 v241, 4, v241
	v_lshrrev_b32_e32 v242, 11, v240
	v_mov_b32_e32 v243, 0x2000
	v_cmp_gt_i32_e64 s[6:7], v243, v222
	s_nop 1
	v_cndmask_b32_e64 v241, v241, v242, s[6:7]
	s_lshl_b32 s6, s92, 8
	s_ashr_i32 s7, s6, 31
	v_lshl_add_u64 v[236:237], s[6:7], 2, v[184:185]
	v_mad_u64_u32 v[236:237], s[6:7], v241, s15, v[236:237]
	v_med3_i32 v224, v222, 0, v238
	v_lshlrev_b32_e32 v224, 2, v224
	global_load_dword v224, v224, s[56:57]
	v_add_u32_e32 v228, 1, v222
	v_med3_i32 v228, v228, 0, v238
	v_lshlrev_b32_e32 v228, 2, v228
	global_load_dword v228, v228, s[56:57]
	v_add_u32_e32 v231, 2, v222
	v_med3_i32 v231, v231, 0, v238
	v_lshlrev_b32_e32 v231, 2, v231
	global_load_dword v231, v231, s[56:57]
	v_add_u32_e32 v233, 3, v222
	v_med3_i32 v233, v233, 0, v238
	v_lshlrev_b32_e32 v233, 2, v233
	global_load_dword v233, v233, s[56:57]
	v_add_u32_e32 v234, 4, v222
	v_med3_i32 v234, v234, 0, v238
	v_lshlrev_b32_e32 v234, 2, v234
	global_load_dword v234, v234, s[56:57]
	v_add_u32_e32 v239, 5, v222
	v_med3_i32 v239, v239, 0, v238
	v_lshlrev_b32_e32 v239, 2, v239
	global_load_dword v239, v239, s[56:57]
	v_add_u32_e32 v252, 6, v222
	v_med3_i32 v252, v252, 0, v238
	v_lshlrev_b32_e32 v252, 2, v252
	global_load_dword v252, v252, s[56:57]
	v_add_u32_e32 v253, 7, v222
	v_med3_i32 v253, v253, 0, v238
	v_lshlrev_b32_e32 v253, 2, v253
	global_load_dword v253, v253, s[56:57]
	global_load_dwordx4 v[240:243], v[236:237], off
	global_load_dwordx4 v[244:247], v[236:237], off offset:16
	global_load_dwordx4 v[248:251], v[236:237], off offset:512
	global_load_dwordx2 v[222:223], v[236:237], off offset:528
	s_nop 0
	global_load_dwordx2 v[236:237], v[236:237], off offset:536
	v_mov_b32_e32 v3, v2
	v_mov_b32_e32 v4, v2
	v_mov_b32_e32 v5, v2
	v_mov_b32_e32 v14, v2
	v_mov_b32_e32 v15, v2
	v_mov_b32_e32 v16, v2
	v_mov_b32_e32 v17, v2
	v_mov_b32_e32 v10, v2
	v_mov_b32_e32 v11, v2
	v_mov_b32_e32 v12, v2
	v_mov_b32_e32 v13, v2
	v_mov_b32_e32 v26, v2
	v_mov_b32_e32 v27, v2
	v_mov_b32_e32 v28, v2
	v_mov_b32_e32 v29, v2
	v_mov_b32_e32 v6, v2
	v_mov_b32_e32 v7, v2
	v_mov_b32_e32 v8, v2
	v_mov_b32_e32 v9, v2
	v_mov_b32_e32 v42, v2
	v_mov_b32_e32 v43, v2
	v_mov_b32_e32 v44, v2
	v_mov_b32_e32 v45, v2
	v_mov_b32_e32 v30, v2
	v_mov_b32_e32 v31, v2
	v_mov_b32_e32 v32, v2
	v_mov_b32_e32 v33, v2
	v_mov_b32_e32 v58, v2
	v_mov_b32_e32 v59, v2
	v_mov_b32_e32 v60, v2
	v_mov_b32_e32 v61, v2
	v_mov_b32_e32 v74, v2
	v_mov_b32_e32 v75, v2
	v_mov_b32_e32 v76, v2
	v_mov_b32_e32 v77, v2
	v_mov_b32_e32 v22, v2
	v_mov_b32_e32 v23, v2
	v_mov_b32_e32 v24, v2
	v_mov_b32_e32 v25, v2
	v_mov_b32_e32 v34, v2
	v_mov_b32_e32 v35, v2
	v_mov_b32_e32 v36, v2
	v_mov_b32_e32 v37, v2
	v_mov_b32_e32 v18, v2
	v_mov_b32_e32 v19, v2
	v_mov_b32_e32 v20, v2
	v_mov_b32_e32 v21, v2
	v_mov_b32_e32 v50, v2
	v_mov_b32_e32 v51, v2
	v_mov_b32_e32 v52, v2
	v_mov_b32_e32 v53, v2
	v_mov_b32_e32 v38, v2
	v_mov_b32_e32 v39, v2
	v_mov_b32_e32 v40, v2
	v_mov_b32_e32 v41, v2
	v_mov_b32_e32 v46, v2
	v_mov_b32_e32 v47, v2
	v_mov_b32_e32 v48, v2
	v_mov_b32_e32 v49, v2
	v_mov_b32_e32 v54, v2
	v_mov_b32_e32 v55, v2
	v_mov_b32_e32 v56, v2
	v_mov_b32_e32 v57, v2
	v_mov_b32_e32 v66, v2
	v_mov_b32_e32 v67, v2
	v_mov_b32_e32 v68, v2
	v_mov_b32_e32 v69, v2
	v_mov_b32_e32 v78, v2
	v_mov_b32_e32 v79, v2
	v_mov_b32_e32 v80, v2
	v_mov_b32_e32 v81, v2
	v_mov_b32_e32 v62, v2
	v_mov_b32_e32 v63, v2
	v_mov_b32_e32 v64, v2
	v_mov_b32_e32 v65, v2
	v_mov_b32_e32 v70, v2
	v_mov_b32_e32 v71, v2
	v_mov_b32_e32 v72, v2
	v_mov_b32_e32 v73, v2
	v_mov_b32_e32 v86, v2
	v_mov_b32_e32 v87, v2
	v_mov_b32_e32 v88, v2
	v_mov_b32_e32 v89, v2
	v_mov_b32_e32 v94, v2
	v_mov_b32_e32 v95, v2
	v_mov_b32_e32 v96, v2
	v_mov_b32_e32 v97, v2
	v_mov_b32_e32 v98, v2
	v_mov_b32_e32 v99, v2
	v_mov_b32_e32 v100, v2
	v_mov_b32_e32 v101, v2
	v_mov_b32_e32 v106, v2
	v_mov_b32_e32 v107, v2
	v_mov_b32_e32 v108, v2
	v_mov_b32_e32 v109, v2
	v_mov_b32_e32 v82, v2
	v_mov_b32_e32 v83, v2
	v_mov_b32_e32 v84, v2
	v_mov_b32_e32 v85, v2
	v_mov_b32_e32 v90, v2
	v_mov_b32_e32 v91, v2
	v_mov_b32_e32 v92, v2
	v_mov_b32_e32 v93, v2
	v_mov_b32_e32 v102, v2
	v_mov_b32_e32 v103, v2
	v_mov_b32_e32 v104, v2
	v_mov_b32_e32 v105, v2
	v_mov_b32_e32 v110, v2
	v_mov_b32_e32 v111, v2
	v_mov_b32_e32 v112, v2
	v_mov_b32_e32 v113, v2
	v_mov_b32_e32 v114, v2
	v_mov_b32_e32 v115, v2
	v_mov_b32_e32 v116, v2
	v_mov_b32_e32 v117, v2
	v_mov_b32_e32 v118, v2
	v_mov_b32_e32 v119, v2
	v_mov_b32_e32 v120, v2
	v_mov_b32_e32 v121, v2
	v_mov_b32_e32 v122, v2
	v_mov_b32_e32 v123, v2
	v_mov_b32_e32 v124, v2
	v_mov_b32_e32 v125, v2
	v_mov_b32_e32 v126, v2
	v_mov_b32_e32 v127, v2
	v_mov_b32_e32 v128, v2
	v_mov_b32_e32 v129, v2
	s_add_u32 s4, s44, 0x100
	s_addc_u32 s5, s45, 0
	s_add_i32 s34, 0, 0x10000
	s_cmp_eq_u32 s31, 28
	s_cselect_b32 s43, s95, s5
	s_cselect_b32 s42, s94, s4
	s_cselect_b32 s7, s27, s30
	s_cselect_b32 s6, s28, s29
	s_add_i32 s35, 0, 0x14000
	v_add_u32_e32 v142, s34, v196
	v_add_u32_e32 v158, s35, v196
	ds_read_b128 v[130:133], v142
	ds_read_b128 v[134:137], v142 offset:1024
	ds_read_b128 v[138:141], v142 offset:2048
	ds_read_b128 v[142:145], v142 offset:3072
	ds_read_b128 v[146:149], v158
	ds_read_b128 v[150:153], v158 offset:1024
	ds_read_b128 v[154:157], v158 offset:2048
	ds_read_b128 v[158:161], v158 offset:3072
	v_lshl_add_u64 v[194:195], s[44:45], 0, v[186:187]
	s_add_i32 m0, s93, 0xc000
	ds_read_b128 v[162:165], v201
	ds_read_b128 v[166:169], v201 offset:1024
	ds_read_b128 v[170:173], v201 offset:2048
	ds_read_b128 v[174:177], v201 offset:3072
	ds_read_b128 v[190:193], v201 offset:4096
	ds_read_b128 v[202:205], v201 offset:5120
	ds_read_b128 v[206:209], v201 offset:6144
	ds_read_b128 v[210:213], v201 offset:7168
	global_load_lds_dwordx4 v[194:195], off
	s_add_i32 m0, s93, 0xe000
	v_lshl_add_u64 v[194:195], s[44:45], 0, v[188:189]
	global_load_lds_dwordx4 v[194:195], off
	s_setprio 1
	s_waitcnt lgkmcnt(0)
	s_barrier
; #define PG8_STAGE(bufoff, gbase, voff) do { _Pragma("unroll") for (int _i = 0; _i < 2; ++_i) \
;         __builtin_amdgcn_global_load_lds((const unsigned*)((const char*)(gbase) + (voff)[_i]), (LAS unsigned*)(lds + (bufoff) + ldsw + _i * 8192), 16, 0, 0); } while (0)
; #define PG8_LDA(dst, b, h) do { _Pragma("unroll") for (int m = 0; m < 4; ++m) _Pragma("unroll") for (int k = 0; k < 2; ++k) dst[m][k] = *(const LAS bf16x8*)(lds + PG8_SA(b, h) + aoff + m * 2048 + k * 1024); } while (0)
; #define PG8_MMA(ai, bj, At, Bt) do { __builtin_amdgcn_s_setprio(1); _Pragma("unroll") for (int m = 0; m < 4; ++m) _Pragma("unroll") for (int n = 0; n < 2; ++n) _Pragma("unroll") for (int k = 0; k < 2; ++k) \
;         acc[ai][bj][m][n] = __builtin_amdgcn_mfma_f32_16x16x32_bf16(Bt[n][k], At[m][k], acc[ai][bj][m][n], 0, 0, 0); __builtin_amdgcn_s_setprio(0); } while (0)
; #define PG8_WAIT_V(n) asm volatile("s_waitcnt vmcnt(" #n ")" ::: "memory")
; #define PG8_WAIT_L(n) asm volatile("s_waitcnt lgkmcnt(" #n ")" ::: "memory")
; #define PG8_BAR __builtin_amdgcn_s_barrier()
; #define PG8_SCHED __builtin_amdgcn_sched_barrier(0)
; template <class Epi, int AMODE>
; __device__ __forceinline__ void gemm_phase(LAS unsigned char* lds, const Gemm g, const StaticOrder& S, const Epi& E, int stagger_us, int tid_in) {
;     ...
;             PG8_WAIT_V(8); PG8_WAIT_L(0); PG8_BAR; PG8_MMA(0, 0, At, B0); PG8_MMA(0, 1, At, B1); PG8_BAR; PG8_SCHED;
;             PG8_LDA(At, 0, 1); PG8_STAGE(PG8_SB(0, 0), b2, voffB); PG8_STAGE(PG8_SB(0, 1), b2 + hstepB, voffB); PG8_STAGE(PG8_SA(0, 0), a2, voffA);
;             PG8_WAIT_V(8); PG8_WAIT_L(0); PG8_BAR; PG8_MMA(1, 0, At, B0); PG8_MMA(1, 1, At, B1); PG8_BAR; PG8_SCHED;
	v_mfma_f32_16x16x32_bf16 v[126:129], v[130:133], v[162:165], v[126:129]
	v_mfma_f32_16x16x32_bf16 v[122:125], v[138:141], v[162:165], v[122:125]
	v_mfma_f32_16x16x32_bf16 v[118:121], v[130:133], v[170:173], v[118:121]
	v_mfma_f32_16x16x32_bf16 v[114:117], v[138:141], v[170:173], v[114:117]
	v_mfma_f32_16x16x32_bf16 v[110:113], v[130:133], v[190:193], v[110:113]
	v_mfma_f32_16x16x32_bf16 v[102:105], v[138:141], v[190:193], v[102:105]
	v_mfma_f32_16x16x32_bf16 v[90:93], v[130:133], v[206:209], v[90:93]
	v_mfma_f32_16x16x32_bf16 v[82:85], v[138:141], v[206:209], v[82:85]
	v_mfma_f32_16x16x32_bf16 v[126:129], v[134:137], v[166:169], v[126:129]
	v_mfma_f32_16x16x32_bf16 v[122:125], v[142:145], v[166:169], v[122:125]
	v_mfma_f32_16x16x32_bf16 v[118:121], v[134:137], v[174:177], v[118:121]
	v_mfma_f32_16x16x32_bf16 v[114:117], v[142:145], v[174:177], v[114:117]
	v_mfma_f32_16x16x32_bf16 v[110:113], v[134:137], v[202:205], v[110:113]
	v_mfma_f32_16x16x32_bf16 v[102:105], v[142:145], v[202:205], v[102:105]
	v_mfma_f32_16x16x32_bf16 v[90:93], v[134:137], v[210:213], v[90:93]
	v_mfma_f32_16x16x32_bf16 v[82:85], v[142:145], v[210:213], v[82:85]
	v_mfma_f32_16x16x32_bf16 v[106:109], v[146:149], v[162:165], v[106:109]
	v_mfma_f32_16x16x32_bf16 v[98:101], v[154:157], v[162:165], v[98:101]
	v_mfma_f32_16x16x32_bf16 v[94:97], v[146:149], v[170:173], v[94:97]
	v_mfma_f32_16x16x32_bf16 v[86:89], v[154:157], v[170:173], v[86:89]
	v_mfma_f32_16x16x32_bf16 v[70:73], v[146:149], v[190:193], v[70:73]
	v_mfma_f32_16x16x32_bf16 v[62:65], v[154:157], v[190:193], v[62:65]
	v_mfma_f32_16x16x32_bf16 v[78:81], v[146:149], v[206:209], v[78:81]
	v_mfma_f32_16x16x32_bf16 v[66:69], v[154:157], v[206:209], v[66:69]
	v_mfma_f32_16x16x32_bf16 v[106:109], v[150:153], v[166:169], v[106:109]
	v_mfma_f32_16x16x32_bf16 v[98:101], v[158:161], v[166:169], v[98:101]
	v_mfma_f32_16x16x32_bf16 v[94:97], v[150:153], v[174:177], v[94:97]
	v_mfma_f32_16x16x32_bf16 v[86:89], v[158:161], v[174:177], v[86:89]
	v_mfma_f32_16x16x32_bf16 v[70:73], v[150:153], v[202:205], v[70:73]
	v_mfma_f32_16x16x32_bf16 v[62:65], v[158:161], v[202:205], v[62:65]
	v_mfma_f32_16x16x32_bf16 v[78:81], v[150:153], v[210:213], v[78:81]
	v_mfma_f32_16x16x32_bf16 v[66:69], v[158:161], v[210:213], v[66:69]
	s_barrier
	s_setprio 0
	s_add_i32 s34, s34, s91
	v_lshl_add_u64 v[194:195], s[6:7], 0, v[0:1]
	s_mov_b32 m0, s34
	ds_read_b128 v[162:165], v201 offset:16384
	ds_read_b128 v[166:169], v201 offset:17408
	ds_read_b128 v[170:173], v201 offset:18432
	ds_read_b128 v[174:177], v201 offset:19456
	ds_read_b128 v[190:193], v201 offset:20480
	ds_read_b128 v[202:205], v201 offset:21504
	ds_read_b128 v[206:209], v201 offset:22528
	ds_read_b128 v[210:213], v201 offset:23552
	global_load_lds_dwordx4 v[194:195], off
	s_add_i32 m0, s34, 0x2000
	s_add_u32 s44, s6, 0x80000
	v_lshl_add_u64 v[214:215], s[6:7], 0, v[182:183]
	s_addc_u32 s45, s7, 0
	s_add_i32 s34, s35, s91
	global_load_lds_dwordx4 v[214:215], off
	v_lshl_add_u64 v[216:217], s[44:45], 0, v[0:1]
	s_mov_b32 m0, s34
	v_lshl_add_u64 v[218:219], s[42:43], 0, v[180:181]
	global_load_lds_dwordx4 v[216:217], off
	s_add_i32 m0, s34, 0x2000
	v_lshl_add_u64 v[216:217], s[44:45], 0, v[182:183]
	global_load_lds_dwordx4 v[216:217], off
	s_mov_b32 m0, s93
	v_lshl_add_u64 v[216:217], s[42:43], 0, v[178:179]
	global_load_lds_dwordx4 v[216:217], off
	s_mov_b32 m0, s83
	s_nop 0
	global_load_lds_dwordx4 v[218:219], off
	s_setprio 1
	s_waitcnt lgkmcnt(0)
	s_barrier
	v_mfma_f32_16x16x32_bf16 v[54:57], v[130:133], v[162:165], v[54:57]
	v_mfma_f32_16x16x32_bf16 v[46:49], v[138:141], v[162:165], v[46:49]
	v_mfma_f32_16x16x32_bf16 v[38:41], v[130:133], v[170:173], v[38:41]
	v_mfma_f32_16x16x32_bf16 v[50:53], v[138:141], v[170:173], v[50:53]
	v_mfma_f32_16x16x32_bf16 v[18:21], v[130:133], v[190:193], v[18:21]
	v_mfma_f32_16x16x32_bf16 v[34:37], v[138:141], v[190:193], v[34:37]
	v_mfma_f32_16x16x32_bf16 v[22:25], v[130:133], v[206:209], v[22:25]
	v_mfma_f32_16x16x32_bf16 v[74:77], v[138:141], v[206:209], v[74:77]
	v_mfma_f32_16x16x32_bf16 v[54:57], v[134:137], v[166:169], v[54:57]
	v_mfma_f32_16x16x32_bf16 v[46:49], v[142:145], v[166:169], v[46:49]
	v_mfma_f32_16x16x32_bf16 v[38:41], v[134:137], v[174:177], v[38:41]
	v_mfma_f32_16x16x32_bf16 v[50:53], v[142:145], v[174:177], v[50:53]
	v_mfma_f32_16x16x32_bf16 v[18:21], v[134:137], v[202:205], v[18:21]
	v_mfma_f32_16x16x32_bf16 v[34:37], v[142:145], v[202:205], v[34:37]
	v_mfma_f32_16x16x32_bf16 v[22:25], v[134:137], v[210:213], v[22:25]
	v_mfma_f32_16x16x32_bf16 v[74:77], v[142:145], v[210:213], v[74:77]
	v_mfma_f32_16x16x32_bf16 v[58:61], v[146:149], v[162:165], v[58:61]
	v_mfma_f32_16x16x32_bf16 v[30:33], v[154:157], v[162:165], v[30:33]
	v_mfma_f32_16x16x32_bf16 v[42:45], v[146:149], v[170:173], v[42:45]
	v_mfma_f32_16x16x32_bf16 v[6:9], v[154:157], v[170:173], v[6:9]
	v_mfma_f32_16x16x32_bf16 v[26:29], v[146:149], v[190:193], v[26:29]
	v_mfma_f32_16x16x32_bf16 v[10:13], v[154:157], v[190:193], v[10:13]
	v_mfma_f32_16x16x32_bf16 v[14:17], v[146:149], v[206:209], v[14:17]
	v_mfma_f32_16x16x32_bf16 v[2:5], v[154:157], v[206:209], v[2:5]
	v_mfma_f32_16x16x32_bf16 v[58:61], v[150:153], v[166:169], v[58:61]
	v_mfma_f32_16x16x32_bf16 v[30:33], v[158:161], v[166:169], v[30:33]
	v_mfma_f32_16x16x32_bf16 v[42:45], v[150:153], v[174:177], v[42:45]
	v_mfma_f32_16x16x32_bf16 v[6:9], v[158:161], v[174:177], v[6:9]
	v_mfma_f32_16x16x32_bf16 v[26:29], v[150:153], v[202:205], v[26:29]
	v_mfma_f32_16x16x32_bf16 v[10:13], v[158:161], v[202:205], v[10:13]
	v_mfma_f32_16x16x32_bf16 v[14:17], v[150:153], v[210:213], v[14:17]
	v_mfma_f32_16x16x32_bf16 v[2:5], v[158:161], v[210:213], v[2:5]
	s_barrier
; #define PG8_STAGE(bufoff, gbase, voff) do { _Pragma("unroll") for (int _i = 0; _i < 2; ++_i) \
;         __builtin_amdgcn_global_load_lds((const unsigned*)((const char*)(gbase) + (voff)[_i]), (LAS unsigned*)(lds + (bufoff) + ldsw + _i * 8192), 16, 0, 0); } while (0)
; #define PG8_LDA(dst, b, h) do { _Pragma("unroll") for (int m = 0; m < 4; ++m) _Pragma("unroll") for (int k = 0; k < 2; ++k) dst[m][k] = *(const LAS bf16x8*)(lds + PG8_SA(b, h) + aoff + m * 2048 + k * 1024); } while (0)
; #define PG8_LDB(dst, b, h) do { _Pragma("unroll") for (int n = 0; n < 2; ++n) _Pragma("unroll") for (int k = 0; k < 2; ++k) dst[n][k] = *(const LAS bf16x8*)(lds + PG8_SB(b, h) + boff + n * 2048 + k * 1024); } while (0)
; #define PG8_MMA(ai, bj, At, Bt) do { __builtin_amdgcn_s_setprio(1); _Pragma("unroll") for (int m = 0; m < 4; ++m) _Pragma("unroll") for (int n = 0; n < 2; ++n) _Pragma("unroll") for (int k = 0; k < 2; ++k) \
;         acc[ai][bj][m][n] = __builtin_amdgcn_mfma_f32_16x16x32_bf16(Bt[n][k], At[m][k], acc[ai][bj][m][n], 0, 0, 0); __builtin_amdgcn_s_setprio(0); } while (0)
; #define PG8_WAIT_V(n) asm volatile("s_waitcnt vmcnt(" #n ")" ::: "memory")
; #define PG8_WAIT_L(n) asm volatile("s_waitcnt lgkmcnt(" #n ")" ::: "memory")
; #define PG8_BAR __builtin_amdgcn_s_barrier()
; #define PG8_SCHED __builtin_amdgcn_sched_barrier(0)
; template <class Epi, int AMODE>
; __device__ __forceinline__ void gemm_phase(LAS unsigned char* lds, const Gemm g, const StaticOrder& S, const Epi& E, int stagger_us, int tid_in) {
;     ...
;             PG8_LDB(B0, 1, 0); PG8_LDB(B1, 1, 1); PG8_SCHED; PG8_LDA(At, 1, 0); PG8_STAGE(PG8_SA(0, 1), a2 + hstepA, voffA);
;             PG8_WAIT_V(8); PG8_WAIT_L(0); PG8_BAR; PG8_MMA(0, 0, At, B0); PG8_MMA(0, 1, At, B1); PG8_BAR; PG8_SCHED;
;             PG8_LDA(At, 1, 1); PG8_STAGE(PG8_SB(1, 0), b3, voffB); PG8_STAGE(PG8_SB(1, 1), b3 + hstepB, voffB); PG8_STAGE(PG8_SA(1, 0), a3, voffA);
;             PG8_WAIT_V(8); PG8_WAIT_L(0); PG8_BAR; PG8_MMA(1, 0, At, B0); PG8_MMA(1, 1, At, B1); PG8_BAR; PG8_SCHED;
	s_setprio 0
	s_add_i32 s34, 0, 0x18000
	s_add_i32 s35, 0, 0x1c000
	v_add_u32_e32 v142, s34, v196
	v_add_u32_e32 v158, s35, v196
	ds_read_b128 v[130:133], v142
	ds_read_b128 v[134:137], v142 offset:1024
	ds_read_b128 v[138:141], v142 offset:2048
	ds_read_b128 v[142:145], v142 offset:3072
	ds_read_b128 v[146:149], v158
	ds_read_b128 v[150:153], v158 offset:1024
	ds_read_b128 v[154:157], v158 offset:2048
	ds_read_b128 v[158:161], v158 offset:3072
	s_add_u32 s42, s42, 0x4000
	s_addc_u32 s43, s43, 0
	s_mov_b32 m0, s79
	v_lshl_add_u64 v[220:221], s[42:43], 0, v[178:179]
	ds_read_b128 v[162:165], v201 offset:32768
	ds_read_b128 v[166:169], v201 offset:33792
	ds_read_b128 v[170:173], v201 offset:34816
	ds_read_b128 v[174:177], v201 offset:35840
	ds_read_b128 v[190:193], v201 offset:36864
	ds_read_b128 v[202:205], v201 offset:37888
	ds_read_b128 v[206:209], v201 offset:38912
	ds_read_b128 v[210:213], v201 offset:39936
	global_load_lds_dwordx4 v[220:221], off
	s_mov_b32 m0, s87
	v_lshl_add_u64 v[220:221], s[42:43], 0, v[180:181]
	global_load_lds_dwordx4 v[220:221], off
	s_setprio 1
	s_waitcnt vmcnt(8) lgkmcnt(0)
	s_barrier
	v_mfma_f32_16x16x32_bf16 v[126:129], v[130:133], v[162:165], v[126:129]
	v_mfma_f32_16x16x32_bf16 v[122:125], v[138:141], v[162:165], v[122:125]
	v_mfma_f32_16x16x32_bf16 v[118:121], v[130:133], v[170:173], v[118:121]
	v_mfma_f32_16x16x32_bf16 v[114:117], v[138:141], v[170:173], v[114:117]
	v_mfma_f32_16x16x32_bf16 v[110:113], v[130:133], v[190:193], v[110:113]
	v_mfma_f32_16x16x32_bf16 v[102:105], v[138:141], v[190:193], v[102:105]
	v_mfma_f32_16x16x32_bf16 v[90:93], v[130:133], v[206:209], v[90:93]
	v_mfma_f32_16x16x32_bf16 v[82:85], v[138:141], v[206:209], v[82:85]
	v_mfma_f32_16x16x32_bf16 v[126:129], v[134:137], v[166:169], v[126:129]
	v_mfma_f32_16x16x32_bf16 v[122:125], v[142:145], v[166:169], v[122:125]
	v_mfma_f32_16x16x32_bf16 v[118:121], v[134:137], v[174:177], v[118:121]
	v_mfma_f32_16x16x32_bf16 v[114:117], v[142:145], v[174:177], v[114:117]
	v_mfma_f32_16x16x32_bf16 v[110:113], v[134:137], v[202:205], v[110:113]
	v_mfma_f32_16x16x32_bf16 v[102:105], v[142:145], v[202:205], v[102:105]
	v_mfma_f32_16x16x32_bf16 v[90:93], v[134:137], v[210:213], v[90:93]
	v_mfma_f32_16x16x32_bf16 v[82:85], v[142:145], v[210:213], v[82:85]
	v_mfma_f32_16x16x32_bf16 v[106:109], v[146:149], v[162:165], v[106:109]
	v_mfma_f32_16x16x32_bf16 v[98:101], v[154:157], v[162:165], v[98:101]
	v_mfma_f32_16x16x32_bf16 v[94:97], v[146:149], v[170:173], v[94:97]
	v_mfma_f32_16x16x32_bf16 v[86:89], v[154:157], v[170:173], v[86:89]
	v_mfma_f32_16x16x32_bf16 v[70:73], v[146:149], v[190:193], v[70:73]
	v_mfma_f32_16x16x32_bf16 v[62:65], v[154:157], v[190:193], v[62:65]
	v_mfma_f32_16x16x32_bf16 v[78:81], v[146:149], v[206:209], v[78:81]
	v_mfma_f32_16x16x32_bf16 v[66:69], v[154:157], v[206:209], v[66:69]
	v_mfma_f32_16x16x32_bf16 v[106:109], v[150:153], v[166:169], v[106:109]
	v_mfma_f32_16x16x32_bf16 v[98:101], v[158:161], v[166:169], v[98:101]
	v_mfma_f32_16x16x32_bf16 v[94:97], v[150:153], v[174:177], v[94:97]
	v_mfma_f32_16x16x32_bf16 v[86:89], v[158:161], v[174:177], v[86:89]
	v_mfma_f32_16x16x32_bf16 v[70:73], v[150:153], v[202:205], v[70:73]
	v_mfma_f32_16x16x32_bf16 v[62:65], v[158:161], v[202:205], v[62:65]
	v_mfma_f32_16x16x32_bf16 v[78:81], v[150:153], v[210:213], v[78:81]
	v_mfma_f32_16x16x32_bf16 v[66:69], v[158:161], v[210:213], v[66:69]
	s_barrier
	s_setprio 0
	s_add_i32 s34, s34, s91
	v_lshl_add_u64 v[194:195], v[194:195], 0, s[74:75]
	s_mov_b32 m0, s34
	ds_read_b128 v[162:165], v201 offset:49152
	ds_read_b128 v[166:169], v201 offset:50176
	ds_read_b128 v[170:173], v201 offset:51200
	ds_read_b128 v[174:177], v201 offset:52224
	ds_read_b128 v[190:193], v201 offset:53248
	ds_read_b128 v[202:205], v201 offset:54272
	ds_read_b128 v[206:209], v201 offset:55296
	ds_read_b128 v[210:213], v201 offset:56320
	global_load_lds_dwordx4 v[194:195], off
	s_add_i32 m0, s34, 0x2000
	s_add_u32 s6, s6, 0x80080
	v_lshl_add_u64 v[194:195], v[214:215], 0, s[74:75]
	s_addc_u32 s7, s7, 0
	s_add_i32 s34, s35, s91
	global_load_lds_dwordx4 v[194:195], off
	s_mov_b32 m0, s34
	v_lshl_add_u64 v[194:195], s[6:7], 0, v[0:1]
	global_load_lds_dwordx4 v[194:195], off
	s_add_i32 m0, s34, 0x2000
	v_lshl_add_u64 v[194:195], s[6:7], 0, v[182:183]
	global_load_lds_dwordx4 v[194:195], off
	s_mov_b32 m0, s67
	v_lshl_add_u64 v[194:195], v[216:217], 0, s[74:75]
	global_load_lds_dwordx4 v[194:195], off
	s_mov_b32 m0, s85
	v_lshl_add_u64 v[194:195], v[218:219], 0, s[74:75]
	global_load_lds_dwordx4 v[194:195], off
	s_setprio 1
	s_waitcnt vmcnt(8) lgkmcnt(0)
	s_barrier
	v_mfma_f32_16x16x32_bf16 v[54:57], v[130:133], v[162:165], v[54:57]
	v_mfma_f32_16x16x32_bf16 v[46:49], v[138:141], v[162:165], v[46:49]
	v_mfma_f32_16x16x32_bf16 v[38:41], v[130:133], v[170:173], v[38:41]
	v_mfma_f32_16x16x32_bf16 v[50:53], v[138:141], v[170:173], v[50:53]
	v_mfma_f32_16x16x32_bf16 v[18:21], v[130:133], v[190:193], v[18:21]
	v_mfma_f32_16x16x32_bf16 v[34:37], v[138:141], v[190:193], v[34:37]
	v_mfma_f32_16x16x32_bf16 v[22:25], v[130:133], v[206:209], v[22:25]
	v_mfma_f32_16x16x32_bf16 v[74:77], v[138:141], v[206:209], v[74:77]
	v_mfma_f32_16x16x32_bf16 v[54:57], v[134:137], v[166:169], v[54:57]
	v_mfma_f32_16x16x32_bf16 v[46:49], v[142:145], v[166:169], v[46:49]
	v_mfma_f32_16x16x32_bf16 v[38:41], v[134:137], v[174:177], v[38:41]
	v_mfma_f32_16x16x32_bf16 v[50:53], v[142:145], v[174:177], v[50:53]
	v_mfma_f32_16x16x32_bf16 v[18:21], v[134:137], v[202:205], v[18:21]
	v_mfma_f32_16x16x32_bf16 v[34:37], v[142:145], v[202:205], v[34:37]
	v_mfma_f32_16x16x32_bf16 v[22:25], v[134:137], v[210:213], v[22:25]
	v_mfma_f32_16x16x32_bf16 v[74:77], v[142:145], v[210:213], v[74:77]
	v_mfma_f32_16x16x32_bf16 v[58:61], v[146:149], v[162:165], v[58:61]
	v_mfma_f32_16x16x32_bf16 v[30:33], v[154:157], v[162:165], v[30:33]
	v_mfma_f32_16x16x32_bf16 v[42:45], v[146:149], v[170:173], v[42:45]
	v_mfma_f32_16x16x32_bf16 v[6:9], v[154:157], v[170:173], v[6:9]
	v_mfma_f32_16x16x32_bf16 v[26:29], v[146:149], v[190:193], v[26:29]
	v_mfma_f32_16x16x32_bf16 v[10:13], v[154:157], v[190:193], v[10:13]
	v_mfma_f32_16x16x32_bf16 v[14:17], v[146:149], v[206:209], v[14:17]
	v_mfma_f32_16x16x32_bf16 v[2:5], v[154:157], v[206:209], v[2:5]
	v_mfma_f32_16x16x32_bf16 v[58:61], v[150:153], v[166:169], v[58:61]
	v_mfma_f32_16x16x32_bf16 v[30:33], v[158:161], v[166:169], v[30:33]
	v_mfma_f32_16x16x32_bf16 v[42:45], v[150:153], v[174:177], v[42:45]
	v_mfma_f32_16x16x32_bf16 v[6:9], v[158:161], v[174:177], v[6:9]
	v_mfma_f32_16x16x32_bf16 v[26:29], v[150:153], v[202:205], v[26:29]
	v_mfma_f32_16x16x32_bf16 v[10:13], v[158:161], v[202:205], v[10:13]
	v_mfma_f32_16x16x32_bf16 v[14:17], v[150:153], v[210:213], v[14:17]
	v_mfma_f32_16x16x32_bf16 v[2:5], v[158:161], v[210:213], v[2:5]
	s_barrier
	s_setprio 0
	s_add_i32 s31, s31, 2
	s_add_u32 s29, s29, 0x100
	s_addc_u32 s30, s30, 0
	s_cmp_gt_u32 s31, 29
	s_mov_b64 s[44:45], s[4:5]
